# attention epilogue merge loop: all 10 loads of a trip issued up front (one wait instead of four), P7 rs loads hoisted
# speedup vs baseline: 1.0028x; 1.0028x over previous
; __device__ __forceinline__ void unit(LAS unsigned char* lds, const Tensors& T, int h, int qrow0, int nact, bool sample, int limbase, int kv0, int kvnew, int nt) {
;     ...
;         for (int i = 0; i < 8; ++i) {
;             const int rr = 4 * i + (lane >> 4); const int R = qrow0 + 32 * wid + rr;
;             const u32x4 yw = *(const LAS u32x4*)(stg + rr * 272 + ch * 16);
;             const u32x4 sw = *(const GAS u32x4*)(T.S1 + (size_t)R * DM + col), gw = *(const GAS u32x4*)(T.GBS + (size_t)R * DM + col), u0w = *(const GAS u32x4*)(T.U + (size_t)R * DM + col);
;             float u1[8], u2[8];
;             int tpos, bl; if (!sample) { tpos = R & (SEQ - 1); bl = 0; } else { tpos = (R - TP) & (DSEQ - 1); bl = (R - TP) >> 6; }
;             if (tpos >= 1) { const u32x4 w = *(const GAS u32x4*)(T.U + (size_t)(R - 1) * DM + col);
;                 u1[0] = bflo(w.x); u1[1] = bfhi(w.x); u1[2] = bflo(w.y); u1[3] = bfhi(w.y); u1[4] = bflo(w.z); u1[5] = bfhi(w.z); u1[6] = bflo(w.w); u1[7] = bfhi(w.w); }
;             else if (sample) { const f32x4 a = *(const GAS f32x4*)(T.state + (size_t)(bl * 2 + 1) * DM + col), b = *(const GAS f32x4*)(T.state + (size_t)(bl * 2 + 1) * DM + col + 4);
;                 u1[0] = a[0]; u1[1] = a[1]; u1[2] = a[2]; u1[3] = a[3]; u1[4] = b[0]; u1[5] = b[1]; u1[6] = b[2]; u1[7] = b[3]; }
;             else {
; #pragma unroll
;                 for (int e = 0; e < 8; ++e) u1[e] = 0.f; }
;             if (tpos >= 2) { const u32x4 w = *(const GAS u32x4*)(T.U + (size_t)(R - 2) * DM + col);
;                 u2[0] = bflo(w.x); u2[1] = bfhi(w.x); u2[2] = bflo(w.y); u2[3] = bfhi(w.y); u2[4] = bflo(w.z); u2[5] = bfhi(w.z); u2[6] = bflo(w.w); u2[7] = bfhi(w.w); }
;             else if (sample) { const int sr = tpos;
;                 const f32x4 a = *(const GAS f32x4*)(T.state + (size_t)(bl * 2 + sr) * DM + col), b = *(const GAS f32x4*)(T.state + (size_t)(bl * 2 + sr) * DM + col + 4);
;                 u2[0] = a[0]; u2[1] = a[1]; u2[2] = a[2]; u2[3] = a[3]; u2[4] = b[0]; u2[5] = b[1]; u2[6] = b[2]; u2[7] = b[3]; }
;             else {
; #pragma unroll
;                 for (int e = 0; e < 8; ++e) u2[e] = 0.f; }
;             const unsigned yv[4] = {yw.x, yw.y, yw.z, yw.w}, sv[4] = {sw.x, sw.y, sw.z, sw.w}, gv[4] = {gw.x, gw.y, gw.z, gw.w}, uv[4] = {u0w.x, u0w.y, u0w.z, u0w.w};
;             unsigned ow[4];
; #pragma unroll
.LBB0_930:
	s_or_b64 exec, exec, s[0:1]
	s_waitcnt vmcnt(8)
	v_pk_mul_f32 v[68:69], v[0:1], v[68:69]
	s_waitcnt vmcnt(0)
	v_lshlrev_b32_e32 v80, 16, v32
	v_and_b32_e32 v81, 0xffff0000, v32
	v_pk_fma_f32 v[64:65], v[8:9], v[64:65], v[68:69]
	v_lshlrev_b32_e32 v76, 16, v28
	v_and_b32_e32 v77, 0xffff0000, v28
	v_pk_fma_f32 v[64:65], v[16:17], v[80:81], v[64:65]
	v_pk_mul_f32 v[68:69], v[2:3], v[70:71]
	s_waitcnt lgkmcnt(0)
	v_lshlrev_b32_e32 v74, 16, v36
	v_and_b32_e32 v75, 0xffff0000, v36
	v_lshlrev_b32_e32 v78, 16, v24
	v_and_b32_e32 v79, 0xffff0000, v24
	v_pk_mul_f32 v[64:65], v[64:65], v[76:77]
	v_lshlrev_b32_e32 v32, 16, v33
	v_and_b32_e32 v33, 0xffff0000, v33
	v_pk_fma_f32 v[60:61], v[10:11], v[60:61], v[68:69]
	v_pk_fma_f32 v[64:65], v[74:75], v[78:79], v[64:65]
	v_lshlrev_b32_e32 v28, 16, v29
	v_and_b32_e32 v29, 0xffff0000, v29
	v_pk_fma_f32 v[32:33], v[18:19], v[32:33], v[60:61]
	v_cvt_pk_bf16_f32 v24, v64, v65
	v_lshlrev_b32_e32 v36, 16, v37
	v_and_b32_e32 v37, 0xffff0000, v37
	v_lshlrev_b32_e32 v64, 16, v25
	v_and_b32_e32 v65, 0xffff0000, v25
	v_pk_mul_f32 v[28:29], v[32:33], v[28:29]
	v_lshlrev_b32_e32 v60, 16, v34
	v_pk_fma_f32 v[28:29], v[36:37], v[64:65], v[28:29]
	v_pk_mul_f32 v[64:65], v[4:5], v[66:67]
	v_and_b32_e32 v61, 0xffff0000, v34
	v_pk_fma_f32 v[58:59], v[12:13], v[58:59], v[64:65]
	v_lshlrev_b32_e32 v32, 16, v30
	v_and_b32_e32 v33, 0xffff0000, v30
	v_pk_fma_f32 v[58:59], v[20:21], v[60:61], v[58:59]
	v_cvt_pk_bf16_f32 v25, v28, v29
	v_lshlrev_b32_e32 v28, 16, v38
	v_and_b32_e32 v29, 0xffff0000, v38
	v_lshlrev_b32_e32 v36, 16, v26
	v_and_b32_e32 v37, 0xffff0000, v26
	v_pk_mul_f32 v[32:33], v[58:59], v[32:33]
	v_lshlrev_b32_e32 v34, 16, v35
	v_pk_fma_f32 v[28:29], v[28:29], v[36:37], v[32:33]
	v_pk_mul_f32 v[36:37], v[6:7], v[62:63]
	v_and_b32_e32 v35, 0xffff0000, v35
	v_pk_fma_f32 v[36:37], v[14:15], v[56:57], v[36:37]
	v_lshlrev_b32_e32 v30, 16, v31
	v_and_b32_e32 v31, 0xffff0000, v31
	v_pk_fma_f32 v[34:35], v[22:23], v[34:35], v[36:37]
	v_cvt_pk_bf16_f32 v26, v28, v29
	v_lshlrev_b32_e32 v28, 16, v39
	v_and_b32_e32 v29, 0xffff0000, v39
	v_lshlrev_b32_e32 v32, 16, v27
	v_and_b32_e32 v33, 0xffff0000, v27
	v_pk_mul_f32 v[30:31], v[34:35], v[30:31]
	v_lshl_add_u64 v[62:63], v[46:47], 0, s[22:23]
	v_pk_fma_f32 v[28:29], v[28:29], v[32:33], v[30:31]
	v_add_u32_e32 v40, 8, v40
	v_cvt_pk_bf16_f32 v27, v28, v29
	v_add_co_u32_e32 v28, vcc, s81, v54
	s_nop 1
	v_addc_co_u32_e32 v29, vcc, 0, v55, vcc
	v_add_co_u32_e32 v32, vcc, s83, v62
	global_store_dwordx4 v[28:29], v[24:27], off
	s_nop 0
	s_nop 0
	s_nop 0
	ds_read_b128 v[58:61], v72 offset:1088
	s_add_u32 s22, s22, 0x4000
	s_addc_u32 s23, s23, 0
	v_add_u32_e32 v72, 0x880, v72
	s_waitcnt lgkmcnt(0)
	v_lshlrev_b32_e32 v74, 16, v58
	v_and_b32_e32 v75, 0xffff0000, v58
	v_lshlrev_b32_e32 v58, 16, v59
	v_and_b32_e32 v59, 0xffff0000, v59
	s_cmp_lg_u32 s22, 0x10000
	v_lshlrev_b32_e32 v64, 16, v108
	v_and_b32_e32 v65, 0xffff0000, v108
	v_lshlrev_b32_e32 v66, 16, v109
	v_and_b32_e32 v67, 0xffff0000, v109
	v_lshlrev_b32_e32 v68, 16, v110
	v_and_b32_e32 v69, 0xffff0000, v110
	v_lshlrev_b32_e32 v70, 16, v111
	v_and_b32_e32 v71, 0xffff0000, v111
	v_lshlrev_b32_e32 v108, 16, v112
	v_and_b32_e32 v109, 0xffff0000, v112
	v_lshlrev_b32_e32 v110, 16, v113
	v_and_b32_e32 v111, 0xffff0000, v113
	v_pk_mul_f32 v[108:109], v[0:1], v[108:109]
	v_pk_mul_f32 v[110:111], v[2:3], v[110:111]
	v_lshlrev_b32_e32 v112, 16, v114
	v_and_b32_e32 v113, 0xffff0000, v114
	v_lshlrev_b32_e32 v80, 16, v124
	v_and_b32_e32 v81, 0xffff0000, v124
	v_pk_fma_f32 v[108:109], v[8:9], v[64:65], v[108:109]
	v_lshlrev_b32_e32 v124, 16, v125
	v_and_b32_e32 v125, 0xffff0000, v125
	v_pk_fma_f32 v[110:111], v[10:11], v[66:67], v[110:111]
	v_lshlrev_b32_e32 v76, 16, v116
	v_and_b32_e32 v77, 0xffff0000, v116
	v_pk_fma_f32 v[108:109], v[16:17], v[80:81], v[108:109]
	v_lshlrev_b32_e32 v116, 16, v117
	v_and_b32_e32 v117, 0xffff0000, v117
	v_pk_fma_f32 v[110:111], v[18:19], v[124:125], v[110:111]
	v_pk_mul_f32 v[112:113], v[4:5], v[112:113]
	v_lshlrev_b32_e32 v78, 16, v120
	v_and_b32_e32 v79, 0xffff0000, v120
	v_pk_mul_f32 v[108:109], v[108:109], v[76:77]
	v_lshlrev_b32_e32 v120, 16, v121
	v_and_b32_e32 v121, 0xffff0000, v121
	v_pk_mul_f32 v[110:111], v[110:111], v[116:117]
	v_lshlrev_b32_e32 v124, 16, v126
	v_and_b32_e32 v125, 0xffff0000, v126
	v_pk_fma_f32 v[112:113], v[12:13], v[68:69], v[112:113]
	v_lshlrev_b32_e32 v114, 16, v115
	v_and_b32_e32 v115, 0xffff0000, v115
	v_pk_fma_f32 v[108:109], v[74:75], v[78:79], v[108:109]
	v_pk_fma_f32 v[110:111], v[58:59], v[120:121], v[110:111]
	v_lshlrev_b32_e32 v116, 16, v118
	v_and_b32_e32 v117, 0xffff0000, v118
	v_pk_fma_f32 v[112:113], v[20:21], v[124:125], v[112:113]
	v_cvt_pk_bf16_f32 v108, v108, v109
	v_cvt_pk_bf16_f32 v109, v110, v111
	v_lshlrev_b32_e32 v110, 16, v60
	v_and_b32_e32 v111, 0xffff0000, v60
	v_lshlrev_b32_e32 v120, 16, v122
	v_and_b32_e32 v121, 0xffff0000, v122
	v_pk_mul_f32 v[112:113], v[112:113], v[116:117]
	v_pk_mul_f32 v[114:115], v[6:7], v[114:115]
	v_pk_fma_f32 v[110:111], v[110:111], v[120:121], v[112:113]
	v_lshlrev_b32_e32 v120, 16, v127
	v_and_b32_e32 v121, 0xffff0000, v127
	v_pk_fma_f32 v[114:115], v[14:15], v[70:71], v[114:115]
	v_lshlrev_b32_e32 v116, 16, v119
	v_and_b32_e32 v117, 0xffff0000, v119
	v_pk_fma_f32 v[114:115], v[22:23], v[120:121], v[114:115]
	v_lshlrev_b32_e32 v112, 16, v61
	v_and_b32_e32 v113, 0xffff0000, v61
	v_lshlrev_b32_e32 v118, 16, v123
	v_and_b32_e32 v119, 0xffff0000, v123
	v_pk_mul_f32 v[114:115], v[114:115], v[116:117]
	v_cvt_pk_bf16_f32 v110, v110, v111
	v_pk_fma_f32 v[112:113], v[112:113], v[118:119], v[114:115]
	s_nop 0
	v_cvt_pk_bf16_f32 v111, v112, v113
	v_add_co_u32_e32 v112, vcc, s81, v62
	s_nop 1
	v_addc_co_u32_e32 v113, vcc, 0, v63, vcc
	global_store_dwordx4 v[112:113], v[108:111], off
	s_cbranch_scc0 .LBB0_935
; #define LAS __attribute__((address_space(3)))
; #define GAS __attribute__((address_space(1)))
; __device__ __forceinline__ float bflo(unsigned w) { return __uint_as_float(w << 16); }
; __device__ __forceinline__ float bfhi(unsigned w) { return __uint_as_float(w & 0xffff0000u); }
; __device__ __forceinline__ void unit(LAS unsigned char* lds, const Tensors& T, int h, int qrow0, int nact, bool sample, int limbase, int kv0, int kvnew, int nt) {
;     ...
;             const int rr = 4 * i + (lane >> 4); const int R = qrow0 + 32 * wid + rr;
;             const u32x4 yw = *(const LAS u32x4*)(stg + rr * 272 + ch * 16);
;             const u32x4 sw = *(const GAS u32x4*)(T.S1 + (size_t)R * DM + col), gw = *(const GAS u32x4*)(T.GBS + (size_t)R * DM + col), u0w = *(const GAS u32x4*)(T.U + (size_t)R * DM + col);
;             float u1[8], u2[8];
;             int tpos, bl; if (!sample) { tpos = R & (SEQ - 1); bl = 0; } else { tpos = (R - TP) & (DSEQ - 1); bl = (R - TP) >> 6; }
;             if (tpos >= 1) { const u32x4 w = *(const GAS u32x4*)(T.U + (size_t)(R - 1) * DM + col);
;                 u1[0] = bflo(w.x); u1[1] = bfhi(w.x); u1[2] = bflo(w.y); u1[3] = bfhi(w.y); u1[4] = bflo(w.z); u1[5] = bfhi(w.z); u1[6] = bflo(w.w); u1[7] = bfhi(w.w); }
;             else if (sample) { const f32x4 a = *(const GAS f32x4*)(T.state + (size_t)(bl * 2 + 1) * DM + col), b = *(const GAS f32x4*)(T.state + (size_t)(bl * 2 + 1) * DM + col + 4);
;                 u1[0] = a[0]; u1[1] = a[1]; u1[2] = a[2]; u1[3] = a[3]; u1[4] = b[0]; u1[5] = b[1]; u1[6] = b[2]; u1[7] = b[3]; }
;             else {
; #pragma unroll
;                 for (int e = 0; e < 8; ++e) u1[e] = 0.f; }
;             if (tpos >= 2) { const u32x4 w = *(const GAS u32x4*)(T.U + (size_t)(R - 2) * DM + col);
;                 u2[0] = bflo(w.x); u2[1] = bfhi(w.x); u2[2] = bflo(w.y); u2[3] = bfhi(w.y); u2[4] = bflo(w.z); u2[5] = bfhi(w.z); u2[6] = bflo(w.w); u2[7] = bfhi(w.w); }
;             else if (sample) { const int sr = tpos;
;                 const f32x4 a = *(const GAS f32x4*)(T.state + (size_t)(bl * 2 + sr) * DM + col), b = *(const GAS f32x4*)(T.state + (size_t)(bl * 2 + sr) * DM + col + 4);
;                 u2[0] = a[0]; u2[1] = a[1]; u2[2] = a[2]; u2[3] = a[3]; u2[4] = b[0]; u2[5] = b[1]; u2[6] = b[2]; u2[7] = b[3]; }
;             else {
; #pragma unroll
;                 for (int e = 0; e < 8; ++e) u2[e] = 0.f; }
.LBB0_931:
	v_lshl_add_u64 v[54:55], v[52:53], 0, s[22:23]
	v_add_co_u32_e32 v24, vcc, 0x2d4c9000, v54
	v_and_b32_e32 v41, 0x7fb, v40
	s_nop 0
	v_addc_co_u32_e32 v25, vcc, 0, v55, vcc
	v_add_co_u32_e32 v26, vcc, 0x358c9000, v54
	v_mov_b32_e32 v68, 0
	s_nop 0
	v_addc_co_u32_e32 v27, vcc, 0, v55, vcc
	v_add_co_u32_e32 v32, vcc, 0x316c9000, v54
	global_load_dwordx4 v[28:31], v[24:25], off
	s_nop 0
	global_load_dwordx4 v[24:27], v[26:27], off
	v_addc_co_u32_e32 v33, vcc, 0, v55, vcc
	global_load_dwordx4 v[32:35], v[32:33], off
	ds_read_b128 v[36:39], v72
	v_lshl_add_u64 v[128:129], v[46:47], 0, s[22:23]
	v_lshl_add_u64 v[130:131], v[44:45], 0, s[22:23]
	v_lshl_add_u64 v[132:133], v[42:43], 0, s[22:23]
	global_load_dwordx4 v[108:111], v[130:131], off
	global_load_dwordx4 v[112:115], v[132:133], off
	v_add_co_u32_e32 v130, vcc, s83, v128
	s_nop 1
	v_addc_co_u32_e32 v131, vcc, 0, v129, vcc
	global_load_dwordx4 v[116:119], v[130:131], off
	v_add_co_u32_e32 v132, vcc, s85, v128
	s_nop 1
	v_addc_co_u32_e32 v133, vcc, 0, v129, vcc
	global_load_dwordx4 v[120:123], v[132:133], off
	v_add_co_u32_e32 v130, vcc, s86, v128
	s_nop 1
	v_addc_co_u32_e32 v131, vcc, 0, v129, vcc
	global_load_dwordx4 v[124:127], v[130:131], off
	v_mov_b32_e32 v64, 0
	v_mov_b32_e32 v65, 0
	v_mov_b32_e32 v60, 0
	v_mov_b32_e32 v61, 0
	v_mov_b32_e32 v58, 0
	v_mov_b32_e32 v59, 0
	v_mov_b32_e32 v56, 0
	v_mov_b32_e32 v57, 0
	v_mov_b32_e32 v69, 0
	v_mov_b32_e32 v70, 0
	v_mov_b32_e32 v71, 0
	v_mov_b32_e32 v66, 0
	v_mov_b32_e32 v67, 0
	v_mov_b32_e32 v62, 0
	v_mov_b32_e32 v63, 0
	v_cmp_ne_u32_e32 vcc, 0, v41
	s_nop 1
	s_and_saveexec_b64 s[0:1], vcc
	v_lshl_add_u64 v[104:105], v[50:51], 0, s[22:23]
	global_load_dwordx4 v[96:99], v[104:105], off
	s_or_b64 exec, exec, s[0:1]
	v_cmp_lt_u32_e32 vcc, 1, v41
	s_nop 1
	s_and_saveexec_b64 s[0:1], vcc
	v_lshl_add_u64 v[106:107], v[48:49], 0, s[22:23]
	global_load_dwordx4 v[100:103], v[106:107], off
	s_or_b64 exec, exec, s[0:1]
	s_waitcnt vmcnt(0)
	v_cmp_ne_u32_e32 vcc, 0, v41
	s_nop 1
	s_and_saveexec_b64 s[0:1], vcc
	v_lshlrev_b32_e32 v64, 16, v96
	v_and_b32_e32 v65, 0xffff0000, v96
	v_lshlrev_b32_e32 v60, 16, v97
	v_and_b32_e32 v61, 0xffff0000, v97
	v_lshlrev_b32_e32 v58, 16, v98
	v_and_b32_e32 v59, 0xffff0000, v98
	v_lshlrev_b32_e32 v56, 16, v99
	v_and_b32_e32 v57, 0xffff0000, v99
	s_or_b64 exec, exec, s[0:1]
	v_cmp_lt_u32_e32 vcc, 1, v41
	s_nop 1
	s_and_saveexec_b64 s[0:1], vcc
	v_lshlrev_b32_e32 v68, 16, v100
	v_and_b32_e32 v69, 0xffff0000, v100
	v_lshlrev_b32_e32 v70, 16, v101
	v_and_b32_e32 v71, 0xffff0000, v101
	v_lshlrev_b32_e32 v66, 16, v102
	v_and_b32_e32 v67, 0xffff0000, v102
	v_lshlrev_b32_e32 v62, 16, v103
	v_and_b32_e32 v63, 0xffff0000, v103
	s_branch .LBB0_930

; __device__ __forceinline__ unsigned pk2(float lo, float hi) { f32x2 v = {lo, hi}; bf16x2_t b = __builtin_convertvector(v, bf16x2_t); return __builtin_bit_cast(unsigned, b); }
;     __device__ __forceinline__ void operator()(const f32x4 (&acc)[2][2][4][2], const Unit& u, int wr, int wc, int fr, int fq) const {
;     ...
;             for (int m = 0; m < 4; ++m) { bf16_t* rowp = O + (size_t)(row0 + ai * HALF + m * 16) * ldc + col0; float rsv = 1.f; if (ACT == 1) rsv = rs[row0 + ai * HALF + m * 16];
; #pragma unroll
;                 for (int bj = 0; bj < 2; ++bj) { f32x4 v0 = acc[ai][bj][m][0], v1 = acc[ai][bj][m][1];
;                     if (ACT == 1) {
; #pragma unroll
;                         for (int j = 0; j < 4; ++j) { const float a = fmaxf(v0[j] * rsv, 0.f), b = fmaxf(v1[j] * rsv, 0.f); v0[j] = a * a; v1[j] = b * b; } }
;                     u32x4 w; w.x = pk2(v0[0], v0[1]); w.y = pk2(v0[2], v0[3]); w.z = pk2(v1[0], v1[1]); w.w = pk2(v1[2], v1[3]);
;                     *(u32x4*)(rowp + bj * HALF) = w; } }
.LBB0_1221:
	v_mov_b32_e32 v138, v206
	s_lshl_b32 s0, s22, 8
	s_add_i32 s0, s0, s60
	v_and_or_b32 v142, v138, 15, s0
	s_lshl_b32 s0, s8, 8
	v_lshrrev_b32_e32 v138, 1, v138
	v_and_or_b32 v138, v138, 24, s0
	v_or_b32_e32 v138, s61, v138
	v_ashrrev_i32_e32 v143, 31, v142
	v_ashrrev_i32_e32 v139, 31, v138
	v_lshlrev_b64 v[140:141], 13, v[142:143]
	v_lshl_add_u64 v[140:141], s[34:35], 0, v[140:141]
	v_lshlrev_b64 v[144:145], 1, v[138:139]
	v_lshl_add_u64 v[138:139], v[140:141], 0, v[144:145]
	v_lshl_add_u64 v[140:141], v[142:143], 2, s[40:41]
	flat_load_dword v143, v[140:141]
	flat_load_dword v214, v[140:141] offset:64
	flat_load_dword v215, v[140:141] offset:128
	flat_load_dword v216, v[140:141] offset:192
	flat_load_dword v217, v[140:141] offset:512
	flat_load_dword v218, v[140:141] offset:576
	flat_load_dword v219, v[140:141] offset:640
	flat_load_dword v220, v[140:141] offset:704
	s_mov_b64 s[0:1], 0x100000
	s_mov_b64 s[22:23], -1
	s_waitcnt vmcnt(0) lgkmcnt(0)
	v_mul_f32_e32 v120, v120, v143
	v_mul_f32_e32 v121, v121, v143
	v_max_f32_e32 v120, 0, v120
	v_max_f32_e32 v121, 0, v121
	v_pk_mul_f32 v[148:149], v[120:121], v[120:121]
	v_mul_f32_e32 v121, v122, v143
	v_mul_f32_e32 v124, v124, v143
	v_mul_f32_e32 v125, v125, v143
	v_mul_f32_e32 v120, v126, v143
	v_max_f32_e32 v122, 0, v121
	v_mul_f32_e32 v121, v127, v143
	v_mul_f32_e32 v123, v123, v143
	v_max_f32_e32 v124, 0, v124
	v_max_f32_e32 v125, 0, v125
	v_max_f32_e32 v120, 0, v120
	v_max_f32_e32 v121, 0, v121
	v_max_f32_e32 v123, 0, v123
	v_pk_mul_f32 v[124:125], v[124:125], v[124:125]
	v_pk_mul_f32 v[126:127], v[120:121], v[120:121]
	v_pk_mul_f32 v[150:151], v[122:123], v[122:123]
	v_mul_f32_e32 v112, v112, v143
	v_mul_f32_e32 v113, v113, v143
	v_cvt_pk_bf16_f32 v120, v124, v125
	v_cvt_pk_bf16_f32 v121, v126, v127
	v_cvt_pk_bf16_f32 v122, v148, v149
	v_cvt_pk_bf16_f32 v123, v150, v151
	v_max_f32_e32 v112, 0, v112
	v_max_f32_e32 v113, 0, v113
	flat_store_dwordx4 v[138:139], v[120:123] sc1
	v_mul_f32_e32 v116, v116, v143
	v_mul_f32_e32 v117, v117, v143
	v_pk_mul_f32 v[120:121], v[112:113], v[112:113]
	v_mul_f32_e32 v113, v114, v143
	v_mul_f32_e32 v112, v118, v143
	v_max_f32_e32 v114, 0, v113
	v_mul_f32_e32 v113, v119, v143
	v_mul_f32_e32 v115, v115, v143
	v_max_f32_e32 v116, 0, v116
	v_max_f32_e32 v117, 0, v117
	v_max_f32_e32 v112, 0, v112
	v_max_f32_e32 v113, 0, v113
	v_max_f32_e32 v115, 0, v115
	v_pk_mul_f32 v[116:117], v[116:117], v[116:117]
	v_pk_mul_f32 v[118:119], v[112:113], v[112:113]
	v_pk_mul_f32 v[122:123], v[114:115], v[114:115]
	v_cvt_pk_bf16_f32 v112, v116, v117
	v_cvt_pk_bf16_f32 v113, v118, v119
	v_cvt_pk_bf16_f32 v114, v120, v121
	v_cvt_pk_bf16_f32 v115, v122, v123
	flat_store_dwordx4 v[138:139], v[112:115] offset:256 sc1
	s_nop 1
	v_or_b32_e32 v114, 16, v142
	v_ashrrev_i32_e32 v115, 31, v114
	v_lshlrev_b64 v[112:113], 13, v[114:115]
	v_lshl_add_u64 v[114:115], v[114:115], 2, s[40:41]
	v_mov_b32_e32 v118, v214
	v_lshl_add_u64 v[112:113], s[34:35], 0, v[112:113]
	v_lshl_add_u64 v[112:113], v[112:113], 0, v[144:145]
	v_mul_f32_e32 v104, v104, v118
	v_mul_f32_e32 v105, v105, v118
	v_max_f32_e32 v104, 0, v104
	v_max_f32_e32 v105, 0, v105
	v_pk_mul_f32 v[114:115], v[104:105], v[104:105]
	v_mul_f32_e32 v105, v106, v118
	v_mul_f32_e32 v108, v108, v118
	v_mul_f32_e32 v109, v109, v118
	v_mul_f32_e32 v104, v110, v118
	v_max_f32_e32 v106, 0, v105
	v_mul_f32_e32 v105, v111, v118
	v_mul_f32_e32 v107, v107, v118
	v_max_f32_e32 v108, 0, v108
	v_max_f32_e32 v109, 0, v109
	v_max_f32_e32 v104, 0, v104
	v_max_f32_e32 v105, 0, v105
	v_max_f32_e32 v107, 0, v107
	v_pk_mul_f32 v[108:109], v[108:109], v[108:109]
	v_pk_mul_f32 v[110:111], v[104:105], v[104:105]
	v_pk_mul_f32 v[116:117], v[106:107], v[106:107]
	v_mul_f32_e32 v96, v96, v118
	v_mul_f32_e32 v97, v97, v118
	v_cvt_pk_bf16_f32 v104, v108, v109
	v_cvt_pk_bf16_f32 v105, v110, v111
	v_cvt_pk_bf16_f32 v106, v114, v115
	v_cvt_pk_bf16_f32 v107, v116, v117
	v_max_f32_e32 v96, 0, v96
	v_max_f32_e32 v97, 0, v97
	flat_store_dwordx4 v[112:113], v[104:107] sc1
	v_mul_f32_e32 v100, v100, v118
	v_mul_f32_e32 v101, v101, v118
	v_pk_mul_f32 v[104:105], v[96:97], v[96:97]
	v_mul_f32_e32 v97, v98, v118
	v_mul_f32_e32 v96, v102, v118
	v_max_f32_e32 v98, 0, v97
	v_mul_f32_e32 v97, v103, v118
	v_mul_f32_e32 v99, v99, v118
	v_max_f32_e32 v100, 0, v100
	v_max_f32_e32 v101, 0, v101
	v_max_f32_e32 v96, 0, v96
	v_max_f32_e32 v97, 0, v97
	v_max_f32_e32 v99, 0, v99
	v_pk_mul_f32 v[100:101], v[100:101], v[100:101]
	v_pk_mul_f32 v[102:103], v[96:97], v[96:97]
	v_pk_mul_f32 v[106:107], v[98:99], v[98:99]
	v_cvt_pk_bf16_f32 v96, v100, v101
	v_cvt_pk_bf16_f32 v97, v102, v103
	v_cvt_pk_bf16_f32 v98, v104, v105
	v_cvt_pk_bf16_f32 v99, v106, v107
	flat_store_dwordx4 v[112:113], v[96:99] offset:256 sc1
	s_nop 1
	v_or_b32_e32 v98, 32, v142
	v_ashrrev_i32_e32 v99, 31, v98
	v_lshlrev_b64 v[96:97], 13, v[98:99]
	v_lshl_add_u64 v[98:99], v[98:99], 2, s[40:41]
	v_mov_b32_e32 v102, v215
	v_lshl_add_u64 v[96:97], s[34:35], 0, v[96:97]
	v_lshl_add_u64 v[96:97], v[96:97], 0, v[144:145]
	v_mul_f32_e32 v88, v88, v102
	v_mul_f32_e32 v89, v89, v102
	v_max_f32_e32 v88, 0, v88
	v_max_f32_e32 v89, 0, v89
	v_pk_mul_f32 v[98:99], v[88:89], v[88:89]
	v_mul_f32_e32 v89, v90, v102
	v_mul_f32_e32 v92, v92, v102
	v_mul_f32_e32 v93, v93, v102
	v_mul_f32_e32 v88, v94, v102
	v_max_f32_e32 v90, 0, v89
	v_mul_f32_e32 v89, v95, v102
	v_mul_f32_e32 v91, v91, v102
	v_max_f32_e32 v92, 0, v92
	v_max_f32_e32 v93, 0, v93
	v_max_f32_e32 v88, 0, v88
	v_max_f32_e32 v89, 0, v89
	v_max_f32_e32 v91, 0, v91
	v_pk_mul_f32 v[92:93], v[92:93], v[92:93]
	v_pk_mul_f32 v[94:95], v[88:89], v[88:89]
; __device__ __forceinline__ unsigned pk2(float lo, float hi) { f32x2 v = {lo, hi}; bf16x2_t b = __builtin_convertvector(v, bf16x2_t); return __builtin_bit_cast(unsigned, b); }
;     __device__ __forceinline__ void operator()(const f32x4 (&acc)[2][2][4][2], const Unit& u, int wr, int wc, int fr, int fq) const {
;     ...
;             for (int m = 0; m < 4; ++m) { bf16_t* rowp = O + (size_t)(row0 + ai * HALF + m * 16) * ldc + col0; float rsv = 1.f; if (ACT == 1) rsv = rs[row0 + ai * HALF + m * 16];
; #pragma unroll
;                 for (int bj = 0; bj < 2; ++bj) { f32x4 v0 = acc[ai][bj][m][0], v1 = acc[ai][bj][m][1];
;                     if (ACT == 1) {
; #pragma unroll
;                         for (int j = 0; j < 4; ++j) { const float a = fmaxf(v0[j] * rsv, 0.f), b = fmaxf(v1[j] * rsv, 0.f); v0[j] = a * a; v1[j] = b * b; } }
;                     u32x4 w; w.x = pk2(v0[0], v0[1]); w.y = pk2(v0[2], v0[3]); w.z = pk2(v1[0], v1[1]); w.w = pk2(v1[2], v1[3]);
;                     *(u32x4*)(rowp + bj * HALF) = w; } }
	v_pk_mul_f32 v[100:101], v[90:91], v[90:91]
	v_mul_f32_e32 v80, v80, v102
	v_mul_f32_e32 v81, v81, v102
	v_cvt_pk_bf16_f32 v88, v92, v93
	v_cvt_pk_bf16_f32 v89, v94, v95
	v_cvt_pk_bf16_f32 v90, v98, v99
	v_cvt_pk_bf16_f32 v91, v100, v101
	v_max_f32_e32 v80, 0, v80
	v_max_f32_e32 v81, 0, v81
	flat_store_dwordx4 v[96:97], v[88:91] sc1
	v_mul_f32_e32 v84, v84, v102
	v_mul_f32_e32 v85, v85, v102
	v_pk_mul_f32 v[88:89], v[80:81], v[80:81]
	v_mul_f32_e32 v81, v82, v102
	v_mul_f32_e32 v80, v86, v102
	v_max_f32_e32 v82, 0, v81
	v_mul_f32_e32 v81, v87, v102
	v_mul_f32_e32 v83, v83, v102
	v_max_f32_e32 v84, 0, v84
	v_max_f32_e32 v85, 0, v85
	v_max_f32_e32 v80, 0, v80
	v_max_f32_e32 v81, 0, v81
	v_max_f32_e32 v83, 0, v83
	v_pk_mul_f32 v[84:85], v[84:85], v[84:85]
	v_pk_mul_f32 v[86:87], v[80:81], v[80:81]
	v_pk_mul_f32 v[90:91], v[82:83], v[82:83]
	v_cvt_pk_bf16_f32 v80, v84, v85
	v_cvt_pk_bf16_f32 v81, v86, v87
	v_cvt_pk_bf16_f32 v82, v88, v89
	v_cvt_pk_bf16_f32 v83, v90, v91
	flat_store_dwordx4 v[96:97], v[80:83] offset:256 sc1
	s_nop 1
	v_or_b32_e32 v82, 48, v142
	v_ashrrev_i32_e32 v83, 31, v82
	v_lshlrev_b64 v[80:81], 13, v[82:83]
	v_lshl_add_u64 v[82:83], v[82:83], 2, s[40:41]
	v_mov_b32_e32 v86, v216
	v_lshl_add_u64 v[80:81], s[34:35], 0, v[80:81]
	v_lshl_add_u64 v[80:81], v[80:81], 0, v[144:145]
	v_mul_f32_e32 v72, v72, v86
	v_mul_f32_e32 v73, v73, v86
	v_max_f32_e32 v72, 0, v72
	v_max_f32_e32 v73, 0, v73
	v_pk_mul_f32 v[82:83], v[72:73], v[72:73]
	v_mul_f32_e32 v73, v74, v86
	v_mul_f32_e32 v76, v76, v86
	v_mul_f32_e32 v77, v77, v86
	v_mul_f32_e32 v72, v78, v86
	v_max_f32_e32 v74, 0, v73
	v_mul_f32_e32 v73, v79, v86
	v_mul_f32_e32 v75, v75, v86
	v_max_f32_e32 v76, 0, v76
	v_max_f32_e32 v77, 0, v77
	v_max_f32_e32 v72, 0, v72
	v_max_f32_e32 v73, 0, v73
	v_max_f32_e32 v75, 0, v75
	v_pk_mul_f32 v[76:77], v[76:77], v[76:77]
	v_pk_mul_f32 v[78:79], v[72:73], v[72:73]
	v_pk_mul_f32 v[84:85], v[74:75], v[74:75]
	v_mul_f32_e32 v64, v64, v86
	v_mul_f32_e32 v65, v65, v86
	v_cvt_pk_bf16_f32 v72, v76, v77
	v_cvt_pk_bf16_f32 v73, v78, v79
	v_cvt_pk_bf16_f32 v74, v82, v83
	v_cvt_pk_bf16_f32 v75, v84, v85
	v_max_f32_e32 v64, 0, v64
	v_max_f32_e32 v65, 0, v65
	flat_store_dwordx4 v[80:81], v[72:75] sc1
	v_mul_f32_e32 v68, v68, v86
	v_mul_f32_e32 v69, v69, v86
	v_pk_mul_f32 v[72:73], v[64:65], v[64:65]
	v_mul_f32_e32 v65, v66, v86
	v_mul_f32_e32 v64, v70, v86
	v_max_f32_e32 v66, 0, v65
	v_mul_f32_e32 v65, v71, v86
	v_mul_f32_e32 v67, v67, v86
	v_max_f32_e32 v68, 0, v68
	v_max_f32_e32 v69, 0, v69
	v_max_f32_e32 v64, 0, v64
	v_max_f32_e32 v65, 0, v65
	v_max_f32_e32 v67, 0, v67
	v_pk_mul_f32 v[68:69], v[68:69], v[68:69]
	v_pk_mul_f32 v[70:71], v[64:65], v[64:65]
	v_pk_mul_f32 v[74:75], v[66:67], v[66:67]
	v_cvt_pk_bf16_f32 v64, v68, v69
	v_cvt_pk_bf16_f32 v65, v70, v71
	v_cvt_pk_bf16_f32 v66, v72, v73
	v_cvt_pk_bf16_f32 v67, v74, v75
	flat_store_dwordx4 v[80:81], v[64:67] offset:256 sc1
	v_mov_b32_e32 v70, v217
	v_mul_f32_e32 v56, v56, v70
	v_mul_f32_e32 v57, v57, v70
	v_max_f32_e32 v56, 0, v56
	v_max_f32_e32 v57, 0, v57
	v_mul_f32_e32 v60, v60, v70
	v_mul_f32_e32 v61, v61, v70
	v_pk_mul_f32 v[66:67], v[56:57], v[56:57]
	v_mul_f32_e32 v57, v58, v70
	v_max_f32_e32 v60, 0, v60
	v_max_f32_e32 v61, 0, v61
	v_mul_f32_e32 v56, v62, v70
	v_max_f32_e32 v58, 0, v57
	v_mul_f32_e32 v57, v63, v70
	v_mul_f32_e32 v59, v59, v70
	v_lshl_add_u64 v[64:65], v[138:139], 0, s[0:1]
	v_pk_mul_f32 v[60:61], v[60:61], v[60:61]
	v_max_f32_e32 v56, 0, v56
	v_max_f32_e32 v57, 0, v57
	v_max_f32_e32 v59, 0, v59
	s_mov_b32 s0, 0x100000
	v_pk_mul_f32 v[62:63], v[56:57], v[56:57]
	v_pk_mul_f32 v[68:69], v[58:59], v[58:59]
	v_cvt_pk_bf16_f32 v56, v60, v61
	v_add_co_u32_e32 v60, vcc, s0, v138
	v_mul_f32_e32 v48, v48, v70
	v_mul_f32_e32 v49, v49, v70
	v_cvt_pk_bf16_f32 v57, v62, v63
	v_cvt_pk_bf16_f32 v58, v66, v67
	v_cvt_pk_bf16_f32 v59, v68, v69
	v_addc_co_u32_e32 v61, vcc, 0, v139, vcc
	v_max_f32_e32 v48, 0, v48
	v_max_f32_e32 v49, 0, v49
	flat_store_dwordx4 v[60:61], v[56:59] sc1
	v_mul_f32_e32 v52, v52, v70
	v_mul_f32_e32 v53, v53, v70
	v_pk_mul_f32 v[56:57], v[48:49], v[48:49]
	v_mul_f32_e32 v49, v50, v70
	v_mul_f32_e32 v48, v54, v70
	v_max_f32_e32 v50, 0, v49
	v_mul_f32_e32 v49, v55, v70
	v_mul_f32_e32 v51, v51, v70
	v_max_f32_e32 v52, 0, v52
	v_max_f32_e32 v53, 0, v53
	v_max_f32_e32 v48, 0, v48
	v_max_f32_e32 v49, 0, v49
	v_max_f32_e32 v51, 0, v51
	v_pk_mul_f32 v[52:53], v[52:53], v[52:53]
	v_pk_mul_f32 v[54:55], v[48:49], v[48:49]
	v_pk_mul_f32 v[58:59], v[50:51], v[50:51]
	v_cvt_pk_bf16_f32 v48, v52, v53
	v_cvt_pk_bf16_f32 v49, v54, v55
	v_cvt_pk_bf16_f32 v50, v56, v57
	v_cvt_pk_bf16_f32 v51, v58, v59
	flat_store_dwordx4 v[64:65], v[48:51] offset:256 sc1
	v_mov_b32_e32 v54, v218
	s_mov_b64 s[0:1], 0x120000
	v_lshl_add_u64 v[48:49], v[138:139], 0, s[0:1]
	s_mov_b32 s0, 0x120000
	v_mul_f32_e32 v40, v40, v54
	v_mul_f32_e32 v41, v41, v54
	v_max_f32_e32 v40, 0, v40
	v_max_f32_e32 v41, 0, v41
	v_mul_f32_e32 v44, v44, v54
	v_mul_f32_e32 v45, v45, v54
	v_pk_mul_f32 v[50:51], v[40:41], v[40:41]
	v_mul_f32_e32 v41, v42, v54
	v_max_f32_e32 v44, 0, v44
; __device__ __forceinline__ unsigned pk2(float lo, float hi) { f32x2 v = {lo, hi}; bf16x2_t b = __builtin_convertvector(v, bf16x2_t); return __builtin_bit_cast(unsigned, b); }
;     __device__ __forceinline__ void operator()(const f32x4 (&acc)[2][2][4][2], const Unit& u, int wr, int wc, int fr, int fq) const {
;     ...
;             for (int m = 0; m < 4; ++m) { bf16_t* rowp = O + (size_t)(row0 + ai * HALF + m * 16) * ldc + col0; float rsv = 1.f; if (ACT == 1) rsv = rs[row0 + ai * HALF + m * 16];
; #pragma unroll
;                 for (int bj = 0; bj < 2; ++bj) { f32x4 v0 = acc[ai][bj][m][0], v1 = acc[ai][bj][m][1];
;                     if (ACT == 1) {
; #pragma unroll
;                         for (int j = 0; j < 4; ++j) { const float a = fmaxf(v0[j] * rsv, 0.f), b = fmaxf(v1[j] * rsv, 0.f); v0[j] = a * a; v1[j] = b * b; } }
;                     u32x4 w; w.x = pk2(v0[0], v0[1]); w.y = pk2(v0[2], v0[3]); w.z = pk2(v1[0], v1[1]); w.w = pk2(v1[2], v1[3]);
;                     *(u32x4*)(rowp + bj * HALF) = w; } }
; template <class Epi, class Sched, bool ALIGN_EPI = false, bool SP2 = false>
; __device__ __forceinline__ void gemm_phase(PG8_LAS unsigned char* lds, const Gemm g, const Sched& S, const Epi& E) {
;     ...
;         if (!has_next) break;
; #pragma unroll
;         for (int a = 0; a < 2; ++a)
; #pragma unroll
;             for (int b = 0; b < 2; ++b)
; #pragma unroll
;                 for (int m = 0; m < 4; ++m)
; #pragma unroll
;                     for (int n = 0; n < 2; ++n) acc[a][b][m][n] = (f32x4){0.f, 0.f, 0.f, 0.f};
	v_max_f32_e32 v45, 0, v45
	v_mul_f32_e32 v40, v46, v54
	v_max_f32_e32 v42, 0, v41
	v_mul_f32_e32 v41, v47, v54
	v_mul_f32_e32 v43, v43, v54
	v_pk_mul_f32 v[44:45], v[44:45], v[44:45]
	v_max_f32_e32 v40, 0, v40
	v_max_f32_e32 v41, 0, v41
	v_max_f32_e32 v43, 0, v43
	v_pk_mul_f32 v[46:47], v[40:41], v[40:41]
	v_pk_mul_f32 v[52:53], v[42:43], v[42:43]
	v_cvt_pk_bf16_f32 v40, v44, v45
	v_add_co_u32_e32 v44, vcc, s0, v138
	v_mul_f32_e32 v32, v32, v54
	v_mul_f32_e32 v33, v33, v54
	v_cvt_pk_bf16_f32 v41, v46, v47
	v_cvt_pk_bf16_f32 v42, v50, v51
	v_cvt_pk_bf16_f32 v43, v52, v53
	v_addc_co_u32_e32 v45, vcc, 0, v139, vcc
	v_max_f32_e32 v32, 0, v32
	v_max_f32_e32 v33, 0, v33
	flat_store_dwordx4 v[44:45], v[40:43] sc1
	v_mul_f32_e32 v36, v36, v54
	v_mul_f32_e32 v37, v37, v54
	v_pk_mul_f32 v[40:41], v[32:33], v[32:33]
	v_mul_f32_e32 v33, v34, v54
	v_mul_f32_e32 v32, v38, v54
	v_max_f32_e32 v34, 0, v33
	v_mul_f32_e32 v33, v39, v54
	v_mul_f32_e32 v35, v35, v54
	v_max_f32_e32 v36, 0, v36
	v_max_f32_e32 v37, 0, v37
	v_max_f32_e32 v32, 0, v32
	v_max_f32_e32 v33, 0, v33
	v_max_f32_e32 v35, 0, v35
	v_pk_mul_f32 v[36:37], v[36:37], v[36:37]
	v_pk_mul_f32 v[38:39], v[32:33], v[32:33]
	v_pk_mul_f32 v[42:43], v[34:35], v[34:35]
	v_cvt_pk_bf16_f32 v32, v36, v37
	v_cvt_pk_bf16_f32 v33, v38, v39
	v_cvt_pk_bf16_f32 v34, v40, v41
	v_cvt_pk_bf16_f32 v35, v42, v43
	flat_store_dwordx4 v[48:49], v[32:35] offset:256 sc1
	v_mov_b32_e32 v38, v219
	s_mov_b64 s[0:1], 0x140000
	v_lshl_add_u64 v[32:33], v[138:139], 0, s[0:1]
	s_mov_b32 s0, 0x140000
	v_mul_f32_e32 v24, v24, v38
	v_mul_f32_e32 v25, v25, v38
	v_max_f32_e32 v24, 0, v24
	v_max_f32_e32 v25, 0, v25
	v_mul_f32_e32 v28, v28, v38
	v_mul_f32_e32 v29, v29, v38
	v_pk_mul_f32 v[34:35], v[24:25], v[24:25]
	v_mul_f32_e32 v25, v26, v38
	v_max_f32_e32 v28, 0, v28
	v_max_f32_e32 v29, 0, v29
	v_mul_f32_e32 v24, v30, v38
	v_max_f32_e32 v26, 0, v25
	v_mul_f32_e32 v25, v31, v38
	v_mul_f32_e32 v27, v27, v38
	v_pk_mul_f32 v[28:29], v[28:29], v[28:29]
	v_max_f32_e32 v24, 0, v24
	v_max_f32_e32 v25, 0, v25
	v_max_f32_e32 v27, 0, v27
	v_pk_mul_f32 v[30:31], v[24:25], v[24:25]
	v_pk_mul_f32 v[36:37], v[26:27], v[26:27]
	v_cvt_pk_bf16_f32 v24, v28, v29
	v_add_co_u32_e32 v28, vcc, s0, v138
	v_mul_f32_e32 v16, v16, v38
	v_mul_f32_e32 v17, v17, v38
	v_cvt_pk_bf16_f32 v25, v30, v31
	v_cvt_pk_bf16_f32 v26, v34, v35
	v_cvt_pk_bf16_f32 v27, v36, v37
	v_addc_co_u32_e32 v29, vcc, 0, v139, vcc
	v_max_f32_e32 v16, 0, v16
	v_max_f32_e32 v17, 0, v17
	flat_store_dwordx4 v[28:29], v[24:27] sc1
	v_mul_f32_e32 v20, v20, v38
	v_mul_f32_e32 v21, v21, v38
	v_pk_mul_f32 v[24:25], v[16:17], v[16:17]
	v_mul_f32_e32 v17, v18, v38
	v_mul_f32_e32 v16, v22, v38
	v_max_f32_e32 v18, 0, v17
	v_mul_f32_e32 v17, v23, v38
	v_mul_f32_e32 v19, v19, v38
	v_max_f32_e32 v20, 0, v20
	v_max_f32_e32 v21, 0, v21
	v_max_f32_e32 v16, 0, v16
	v_max_f32_e32 v17, 0, v17
	v_max_f32_e32 v19, 0, v19
	v_pk_mul_f32 v[20:21], v[20:21], v[20:21]
	v_pk_mul_f32 v[22:23], v[16:17], v[16:17]
	v_pk_mul_f32 v[26:27], v[18:19], v[18:19]
	v_cvt_pk_bf16_f32 v16, v20, v21
	v_cvt_pk_bf16_f32 v17, v22, v23
	v_cvt_pk_bf16_f32 v18, v24, v25
	v_cvt_pk_bf16_f32 v19, v26, v27
	flat_store_dwordx4 v[32:33], v[16:19] offset:256 sc1
	v_mov_b32_e32 v22, v220
	s_mov_b64 s[0:1], 0x160000
	v_lshl_add_u64 v[16:17], v[138:139], 0, s[0:1]
	s_mov_b32 s0, 0x160000
	v_mul_f32_e32 v8, v8, v22
	v_mul_f32_e32 v9, v9, v22
	v_max_f32_e32 v8, 0, v8
	v_max_f32_e32 v9, 0, v9
	v_mul_f32_e32 v12, v12, v22
	v_mul_f32_e32 v13, v13, v22
	v_pk_mul_f32 v[18:19], v[8:9], v[8:9]
	v_mul_f32_e32 v9, v10, v22
	v_max_f32_e32 v12, 0, v12
	v_max_f32_e32 v13, 0, v13
	v_mul_f32_e32 v8, v14, v22
	v_max_f32_e32 v10, 0, v9
	v_mul_f32_e32 v9, v15, v22
	v_mul_f32_e32 v11, v11, v22
	v_pk_mul_f32 v[12:13], v[12:13], v[12:13]
	v_max_f32_e32 v8, 0, v8
	v_max_f32_e32 v9, 0, v9
	v_max_f32_e32 v11, 0, v11
	v_pk_mul_f32 v[14:15], v[8:9], v[8:9]
	v_pk_mul_f32 v[20:21], v[10:11], v[10:11]
	v_cvt_pk_bf16_f32 v8, v12, v13
	v_add_co_u32_e32 v12, vcc, s0, v138
	v_mul_f32_e32 v0, v0, v22
	v_mul_f32_e32 v1, v1, v22
	v_cvt_pk_bf16_f32 v9, v14, v15
	v_cvt_pk_bf16_f32 v10, v18, v19
	v_cvt_pk_bf16_f32 v11, v20, v21
	v_addc_co_u32_e32 v13, vcc, 0, v139, vcc
	v_max_f32_e32 v0, 0, v0
	v_max_f32_e32 v1, 0, v1
	flat_store_dwordx4 v[12:13], v[8:11] sc1
	v_mul_f32_e32 v4, v4, v22
	v_mul_f32_e32 v5, v5, v22
	v_pk_mul_f32 v[8:9], v[0:1], v[0:1]
	v_mul_f32_e32 v1, v2, v22
	v_mul_f32_e32 v0, v6, v22
	v_max_f32_e32 v2, 0, v1
	v_mul_f32_e32 v1, v7, v22
	v_mul_f32_e32 v3, v3, v22
	v_max_f32_e32 v4, 0, v4
	v_max_f32_e32 v5, 0, v5
	v_max_f32_e32 v0, 0, v0
	v_max_f32_e32 v1, 0, v1
	v_max_f32_e32 v3, 0, v3
	v_pk_mul_f32 v[4:5], v[4:5], v[4:5]
	v_pk_mul_f32 v[6:7], v[0:1], v[0:1]
	v_pk_mul_f32 v[10:11], v[2:3], v[2:3]
	v_cvt_pk_bf16_f32 v0, v4, v5
	v_cvt_pk_bf16_f32 v1, v6, v7
	v_cvt_pk_bf16_f32 v2, v8, v9
	v_cvt_pk_bf16_f32 v3, v10, v11
	s_andn2_b64 vcc, exec, s[38:39]
	flat_store_dwordx4 v[16:17], v[0:3] offset:256 sc1
	s_cbranch_vccnz .LBB0_1214
	s_andn2_b64 vcc, exec, s[30:31]
	s_cbranch_vccnz .LBB0_1213
	s_barrier
	s_branch .LBB0_1213
